# scan: priority raise on the OLDER producer wave of each SIMD (waves 1-3) instead of waves 5-7 (branch-polarity change only)
# baseline (speedup 1.0000x reference)
; __device__ __forceinline__ void lds_barrier() { asm volatile("s_waitcnt lgkmcnt(0)" ::: "memory"); __builtin_amdgcn_s_barrier(); asm volatile("" ::: "memory"); }
; __device__ __forceinline__ void phase_scan2(const Params& p, int l, LAS unsigned char* lds) {
;     ...
;         if (wid >= 3) { pload(pw); pbuild(pw, lds + pw * SC_SLOT, scr, SC_NP + pw); }
;         lds_barrier();
;         for (int rd = 0; rd < NRD; ++rd) {
;             if (wid == 0) {
; #pragma unroll 1
;                 for (int q = 0; q < SC_NP; ++q) { const int c = rd * SC_NP + q; if (c < NCH) consume(c, lds + ((rd & 1) * SC_NP + q) * SC_SLOT); }
;             } else if (wid >= 3) {
;                 const int cb = (rd + 1) * SC_NP + pw, cn = cb + SC_NP;
;                 if (cb < NCH) pbuild(cb, lds + (((rd + 1) & 1) * SC_NP + pw) * SC_SLOT, scr, cn < NCH ? cn : -1);
.Lsc_producer:
	s_sub_u32 s55, s25, 1
	s_cmp_gt_u32 s25, 4
	s_cselect_b32 s0, 1, 0
	s_sub_u32 s55, s55, s0
	s_cmp_gt_u32 s25, 4
	s_cbranch_scc1 .Lsc_p_noprio
	s_setprio 1
